# ph_post short-conv loop rewritten by hand: all 30 row loads of an item issued together instead of one serialized load+wait per tap
# speedup vs baseline: 1.0294x; 1.0294x over previous
.LBB0_826:
	s_cmpk_gt_i32 s1, 0xfff
	v_readlane_b32 s84, v255, 0
	v_readlane_b32 s2, v255, 2
	v_readlane_b32 s61, v255, 10
	v_readlane_b32 s3, v255, 3
	s_cbranch_scc1 .LBB0_889
	v_readlane_b32 s0, v255, 21
	v_readlane_b32 s4, v255, 38
	v_readlane_b32 s5, v255, 39
	v_readlane_b32 s6, v255, 40
	v_readlane_b32 s7, v255, 41
	s_nop 1
	s_mul_i32 s2, s0, 0x2400
	s_add_u32 s28, s4, s2
	s_addc_u32 s29, s5, 0
	s_mul_i32 s2, s0, 0xc00
	s_add_u32 s30, s6, s2
	s_addc_u32 s31, s7, 0
	s_add_u32 s40, s28, 0x1800
	s_addc_u32 s41, s29, 0
	s_add_u32 s24, s50, 0xb400000
	s_addc_u32 s25, s51, 0
	s_and_b32 s0, s1, 3
	s_lshl_b32 s0, s0, 6
	v_or_b32_e32 v55, s0, v58
	v_lshlrev_b32_e32 v15, 2, v55
	v_lshlrev_b32_e32 v2, 1, v55
	global_load_dword v3, v15, s[28:29]
	global_load_dword v4, v15, s[28:29] offset:3072
	global_load_dword v5, v15, s[40:41]
	global_load_dword v6, v15, s[30:31]
	global_load_dword v7, v15, s[28:29] offset:1024
	global_load_dword v8, v15, s[40:41] offset:-2048
	global_load_dword v9, v15, s[40:41] offset:1024
	global_load_dword v10, v15, s[30:31] offset:1024
	global_load_dword v11, v15, s[28:29] offset:2048
	global_load_dword v12, v15, s[40:41] offset:-1024
	global_load_dword v13, v15, s[40:41] offset:2048
	global_load_dword v14, v15, s[30:31] offset:2048
	s_mov_b32 s3, s1
.Lsc_item:
	s_lshr_b32 s33, s3, 2
	s_lshl_b32 s34, s33, 3
	s_movk_i32 s35, 0x800
	s_movk_i32 s43, 12
	s_cmpk_gt_i32 s34, 0xfff
	s_cselect_b32 s35, s35, 0x100
	s_cselect_b32 s43, s43, 9
	s_add_i32 s36, s35, -1
	s_andn2_b32 s37, s34, s36
	s_and_b32 s36, s34, s36
	s_cmp_lg_u32 s36, 0
	s_cselect_b32 s38, -1, 0
	s_add_i32 s39, s36, 8
	s_cmp_lg_u32 s39, s35
	s_cselect_b32 s39, -1, 0
	s_add_i32 s42, s34, -1
	s_mul_hi_i32 s44, s42, 0x1400
	s_mul_i32 s42, s42, 0x1400
	s_add_u32 s4, s46, s42
	s_addc_u32 s5, s47, s44
	s_add_u32 s6, s4, 0x1400
	s_addc_u32 s7, s5, 0
	s_add_u32 s8, s6, 0x1400
	s_addc_u32 s9, s7, 0
	s_add_u32 s10, s8, 0x1400
	s_addc_u32 s11, s9, 0
	s_add_u32 s12, s10, 0x1400
	s_addc_u32 s13, s11, 0
	s_add_u32 s14, s12, 0x1400
	s_addc_u32 s15, s13, 0
	s_add_u32 s16, s14, 0x1400
	s_addc_u32 s17, s15, 0
	s_add_u32 s18, s16, 0x1400
	s_addc_u32 s19, s17, 0
	s_add_u32 s20, s18, 0x1400
	s_addc_u32 s21, s19, 0
	s_add_u32 s22, s20, 0x1400
	s_addc_u32 s23, s21, 0
	global_load_ushort v16, v2, s[4:5]
	global_load_ushort v26, v2, s[4:5] offset:512
	global_load_ushort v36, v2, s[4:5] offset:1024
	global_load_ushort v17, v2, s[6:7]
	global_load_ushort v27, v2, s[6:7] offset:512
	global_load_ushort v37, v2, s[6:7] offset:1024
	global_load_ushort v18, v2, s[8:9]
	global_load_ushort v28, v2, s[8:9] offset:512
	global_load_ushort v38, v2, s[8:9] offset:1024
	global_load_ushort v19, v2, s[10:11]
	global_load_ushort v29, v2, s[10:11] offset:512
	global_load_ushort v39, v2, s[10:11] offset:1024
	global_load_ushort v20, v2, s[12:13]
	global_load_ushort v30, v2, s[12:13] offset:512
	global_load_ushort v40, v2, s[12:13] offset:1024
	global_load_ushort v21, v2, s[14:15]
	global_load_ushort v31, v2, s[14:15] offset:512
	global_load_ushort v41, v2, s[14:15] offset:1024
	global_load_ushort v22, v2, s[16:17]
	global_load_ushort v32, v2, s[16:17] offset:512
	global_load_ushort v42, v2, s[16:17] offset:1024
	global_load_ushort v23, v2, s[18:19]
	global_load_ushort v33, v2, s[18:19] offset:512
	global_load_ushort v43, v2, s[18:19] offset:1024
	global_load_ushort v24, v2, s[20:21]
	global_load_ushort v34, v2, s[20:21] offset:512
	global_load_ushort v44, v2, s[20:21] offset:1024
	global_load_ushort v25, v2, s[22:23]
	global_load_ushort v35, v2, s[22:23] offset:512
	global_load_ushort v45, v2, s[22:23] offset:1024
	s_lshl_b32 s42, s37, 9
	s_lshl_b32 s44, s36, 1
	s_add_i32 s42, s42, s44
	s_add_u32 s26, s24, s42
	s_addc_u32 s27, s25, 0
	s_add_u32 s4, s26, 0x800000
	s_addc_u32 s5, s27, 0
	v_lshlrev_b32_e32 v54, s43, v55
	s_waitcnt vmcnt(0)
	v_and_b32_e32 v16, s38, v16
	v_and_b32_e32 v25, s39, v25
	v_and_b32_e32 v26, s38, v26
	v_and_b32_e32 v35, s39, v35
	v_and_b32_e32 v36, s38, v36
	v_and_b32_e32 v45, s39, v45
	v_lshlrev_b32_e32 v16, 16, v16
	v_lshlrev_b32_e32 v17, 16, v17
	v_lshlrev_b32_e32 v18, 16, v18
	v_lshlrev_b32_e32 v19, 16, v19
	v_lshlrev_b32_e32 v20, 16, v20
	v_lshlrev_b32_e32 v21, 16, v21
	v_lshlrev_b32_e32 v22, 16, v22
	v_lshlrev_b32_e32 v23, 16, v23
	v_lshlrev_b32_e32 v24, 16, v24
	v_lshlrev_b32_e32 v25, 16, v25
	v_lshlrev_b32_e32 v26, 16, v26
	v_lshlrev_b32_e32 v27, 16, v27
	v_lshlrev_b32_e32 v28, 16, v28
	v_lshlrev_b32_e32 v29, 16, v29
	v_lshlrev_b32_e32 v30, 16, v30
	v_lshlrev_b32_e32 v31, 16, v31
	v_lshlrev_b32_e32 v32, 16, v32
	v_lshlrev_b32_e32 v33, 16, v33
	v_lshlrev_b32_e32 v34, 16, v34
	v_lshlrev_b32_e32 v35, 16, v35
	v_lshlrev_b32_e32 v36, 16, v36
	v_lshlrev_b32_e32 v37, 16, v37
	v_lshlrev_b32_e32 v38, 16, v38
	v_lshlrev_b32_e32 v39, 16, v39
	v_lshlrev_b32_e32 v40, 16, v40
	v_lshlrev_b32_e32 v41, 16, v41
	v_lshlrev_b32_e32 v42, 16, v42
	v_lshlrev_b32_e32 v43, 16, v43
	v_lshlrev_b32_e32 v44, 16, v44
	v_lshlrev_b32_e32 v45, 16, v45
	v_mul_f32_e32 v16, v16, v3
	v_fmac_f32_e32 v16, v17, v4
	v_fmac_f32_e32 v16, v18, v5
	v_add_f32_e32 v16, v16, v6
	v_mul_f32_e32 v17, v17, v3
	v_fmac_f32_e32 v17, v18, v4
	v_fmac_f32_e32 v17, v19, v5
	v_add_f32_e32 v17, v17, v6
	v_mul_f32_e32 v18, v18, v3
	v_fmac_f32_e32 v18, v19, v4
	v_fmac_f32_e32 v18, v20, v5
	v_add_f32_e32 v18, v18, v6
	v_mul_f32_e32 v19, v19, v3
	v_fmac_f32_e32 v19, v20, v4
	v_fmac_f32_e32 v19, v21, v5
	v_add_f32_e32 v19, v19, v6
	v_mul_f32_e32 v20, v20, v3
	v_fmac_f32_e32 v20, v21, v4
	v_fmac_f32_e32 v20, v22, v5
	v_add_f32_e32 v20, v20, v6
	v_mul_f32_e32 v21, v21, v3
	v_fmac_f32_e32 v21, v22, v4
	v_fmac_f32_e32 v21, v23, v5
	v_add_f32_e32 v21, v21, v6
	v_mul_f32_e32 v22, v22, v3
	v_fmac_f32_e32 v22, v23, v4
	v_fmac_f32_e32 v22, v24, v5
	v_add_f32_e32 v22, v22, v6
	v_mul_f32_e32 v23, v23, v3
	v_fmac_f32_e32 v23, v24, v4
	v_fmac_f32_e32 v23, v25, v5
	v_add_f32_e32 v23, v23, v6
	v_mul_f32_e32 v26, v26, v7
	v_fmac_f32_e32 v26, v27, v8
	v_fmac_f32_e32 v26, v28, v9
	v_add_f32_e32 v26, v26, v10
	v_mul_f32_e32 v27, v27, v7
	v_fmac_f32_e32 v27, v28, v8
	v_fmac_f32_e32 v27, v29, v9
	v_add_f32_e32 v27, v27, v10
	v_mul_f32_e32 v28, v28, v7
	v_fmac_f32_e32 v28, v29, v8
	v_fmac_f32_e32 v28, v30, v9
	v_add_f32_e32 v28, v28, v10
	v_mul_f32_e32 v29, v29, v7
	v_fmac_f32_e32 v29, v30, v8
	v_fmac_f32_e32 v29, v31, v9
	v_add_f32_e32 v29, v29, v10
	v_mul_f32_e32 v30, v30, v7
	v_fmac_f32_e32 v30, v31, v8
	v_fmac_f32_e32 v30, v32, v9
	v_add_f32_e32 v30, v30, v10
	v_mul_f32_e32 v31, v31, v7
	v_fmac_f32_e32 v31, v32, v8
	v_fmac_f32_e32 v31, v33, v9
	v_add_f32_e32 v31, v31, v10
	v_mul_f32_e32 v32, v32, v7
	v_fmac_f32_e32 v32, v33, v8
	v_fmac_f32_e32 v32, v34, v9
	v_add_f32_e32 v32, v32, v10
	v_mul_f32_e32 v33, v33, v7
	v_fmac_f32_e32 v33, v34, v8
	v_fmac_f32_e32 v33, v35, v9
	v_add_f32_e32 v33, v33, v10
	v_mul_f32_e32 v36, v36, v11
	v_fmac_f32_e32 v36, v37, v12
	v_fmac_f32_e32 v36, v38, v13
	v_add_f32_e32 v36, v36, v14
	v_mul_f32_e32 v37, v37, v11
	v_fmac_f32_e32 v37, v38, v12
	v_fmac_f32_e32 v37, v39, v13
	v_add_f32_e32 v37, v37, v14
	v_mul_f32_e32 v38, v38, v11
	v_fmac_f32_e32 v38, v39, v12
	v_fmac_f32_e32 v38, v40, v13
	v_add_f32_e32 v38, v38, v14
	v_mul_f32_e32 v39, v39, v11
	v_fmac_f32_e32 v39, v40, v12
	v_fmac_f32_e32 v39, v41, v13
	v_add_f32_e32 v39, v39, v14
	v_mul_f32_e32 v40, v40, v11
	v_fmac_f32_e32 v40, v41, v12
	v_fmac_f32_e32 v40, v42, v13
	v_add_f32_e32 v40, v40, v14
	v_mul_f32_e32 v41, v41, v11
	v_fmac_f32_e32 v41, v42, v12
	v_fmac_f32_e32 v41, v43, v13
	v_add_f32_e32 v41, v41, v14
	v_mul_f32_e32 v42, v42, v11
	v_fmac_f32_e32 v42, v43, v12
	v_fmac_f32_e32 v42, v44, v13
	v_add_f32_e32 v42, v42, v14
	v_mul_f32_e32 v43, v43, v11
	v_fmac_f32_e32 v43, v44, v12
	v_fmac_f32_e32 v43, v45, v13
	v_add_f32_e32 v43, v43, v14
	v_mul_f32_e32 v26, v26, v36
	v_mul_f32_e32 v27, v27, v37
	v_mul_f32_e32 v28, v28, v38
	v_mul_f32_e32 v29, v29, v39
	v_mul_f32_e32 v30, v30, v40
	v_mul_f32_e32 v31, v31, v41
	v_mul_f32_e32 v32, v32, v42
	v_mul_f32_e32 v33, v33, v43
	v_cvt_pk_bf16_f32 v46, v26, v27
	v_cvt_pk_bf16_f32 v47, v28, v29
	v_cvt_pk_bf16_f32 v48, v30, v31
	v_cvt_pk_bf16_f32 v49, v32, v33
	v_cvt_pk_bf16_f32 v50, v16, v17
	v_cvt_pk_bf16_f32 v51, v18, v19
	v_cvt_pk_bf16_f32 v52, v20, v21
	v_cvt_pk_bf16_f32 v53, v22, v23
	global_store_dwordx4 v54, v[46:49], s[26:27]
	global_store_dwordx4 v54, v[50:53], s[4:5]
	s_add_i32 s3, s3, s68
	s_cmpk_lt_i32 s3, 0x1000
	s_cbranch_scc1 .Lsc_item
